# hand-written hierarchical grid barrier, acquire invalidate issued at arrival
# speedup vs baseline: 1.0501x; 1.0240x over previous
.LBB0_94:
	s_waitcnt lgkmcnt(0)
	s_mov_b32 s2, s91
	s_mov_b32 s4, 0
	s_waitcnt vmcnt(0)
	s_mov_b32 s5, 0
	v_or_b32_e32 v0, s2, v230
	v_cmp_eq_u32_e32 vcc, 0, v0
	s_barrier
	s_and_saveexec_b64 s[2:3], vcc
	s_cbranch_execz .LBB0_138
	v_writelane_b32 v2, s4, 1
	v_writelane_b32 v2, s5, 2
	v_writelane_b32 v2, s6, 3
	v_writelane_b32 v2, s7, 4
	v_readlane_b32 s4, v251, 0
	v_readlane_b32 s5, v251, 1
	s_getreg_b32 s6, hwreg(HW_REG_XCC_ID, 0, 4)
	s_load_dword s7, s[4:5], 0x100
	s_load_dwordx2 s[4:5], s[4:5], 0xf0
	v_mov_b32_e32 v0, 0x20010
	ds_read_b32 v3, v0
	ds_read_b32 v4, v0 offset:4
	ds_read_b32 v5, v0 offset:8
	s_and_b32 s6, s6, 15
	s_lshl_b32 s6, s6, 8
	v_mov_b32_e32 v13, 0x3400
	v_mov_b32_e32 v8, 1
	v_mov_b32_e32 v14, 0
	s_waitcnt lgkmcnt(0)
	s_add_u32 s4, s4, 0xee42000
	s_addc_u32 s5, s5, 0
	v_mov_b32_e32 v6, s6
	v_add_u32_e32 v7, 0x400, v6
	v_add_u32_e32 v6, 0x1400, v6
	v_cmp_ne_u32_e32 vcc, 0, v3
	s_cbranch_vccnz .Lhb_have_1
	v_mov_b32_e32 v15, 0x400
.Lhb_cnt_1:
	global_load_dword v16, v15, s[4:5] sc1
	global_load_dword v17, v15, s[4:5] offset:256 sc1
	global_load_dword v18, v15, s[4:5] offset:512 sc1
	global_load_dword v19, v15, s[4:5] offset:768 sc1
	global_load_dword v20, v15, s[4:5] offset:1024 sc1
	global_load_dword v21, v15, s[4:5] offset:1280 sc1
	global_load_dword v22, v15, s[4:5] offset:1536 sc1
	global_load_dword v23, v15, s[4:5] offset:1792 sc1
	global_load_dword v24, v15, s[4:5] offset:2048 sc1
	global_load_dword v25, v15, s[4:5] offset:2304 sc1
	global_load_dword v26, v15, s[4:5] offset:2560 sc1
	global_load_dword v27, v15, s[4:5] offset:2816 sc1
	global_load_dword v28, v15, s[4:5] offset:3072 sc1
	global_load_dword v29, v15, s[4:5] offset:3328 sc1
	global_load_dword v30, v15, s[4:5] offset:3584 sc1
	global_load_dword v31, v15, s[4:5] offset:3840 sc1
	s_waitcnt vmcnt(0)
	v_add3_u32 v3, v16, v17, v18
	v_add3_u32 v3, v3, v19, v20
	v_add3_u32 v3, v3, v21, v22
	v_add3_u32 v3, v3, v23, v24
	v_add3_u32 v3, v3, v25, v26
	v_add3_u32 v3, v3, v27, v28
	v_add3_u32 v3, v3, v29, v30
	v_add_u32_e32 v3, v3, v31
	v_cmp_eq_u32_e32 vcc, s7, v3
	s_cbranch_vccnz .Lhb_cntok_1
	v_add_u32_e32 v14, 1, v14
	s_sleep 1
	v_cmp_gt_u32_e32 vcc, 0x8000, v14
	s_cbranch_vccnz .Lhb_cnt_1
.Lhb_cntok_1:
	v_mov_b32_e32 v4, 0
	v_cmp_ne_u32_e32 vcc, 0, v16
	s_nop 1
	v_addc_co_u32_e32 v4, vcc, 0, v4, vcc
	v_cmp_ne_u32_e32 vcc, 0, v17
	s_nop 1
	v_addc_co_u32_e32 v4, vcc, 0, v4, vcc
	v_cmp_ne_u32_e32 vcc, 0, v18
	s_nop 1
	v_addc_co_u32_e32 v4, vcc, 0, v4, vcc
	v_cmp_ne_u32_e32 vcc, 0, v19
	s_nop 1
	v_addc_co_u32_e32 v4, vcc, 0, v4, vcc
	v_cmp_ne_u32_e32 vcc, 0, v20
	s_nop 1
	v_addc_co_u32_e32 v4, vcc, 0, v4, vcc
	v_cmp_ne_u32_e32 vcc, 0, v21
	s_nop 1
	v_addc_co_u32_e32 v4, vcc, 0, v4, vcc
	v_cmp_ne_u32_e32 vcc, 0, v22
	s_nop 1
	v_addc_co_u32_e32 v4, vcc, 0, v4, vcc
	v_cmp_ne_u32_e32 vcc, 0, v23
	s_nop 1
	v_addc_co_u32_e32 v4, vcc, 0, v4, vcc
	v_cmp_ne_u32_e32 vcc, 0, v24
	s_nop 1
	v_addc_co_u32_e32 v4, vcc, 0, v4, vcc
	v_cmp_ne_u32_e32 vcc, 0, v25
	s_nop 1
	v_addc_co_u32_e32 v4, vcc, 0, v4, vcc
	v_cmp_ne_u32_e32 vcc, 0, v26
	s_nop 1
	v_addc_co_u32_e32 v4, vcc, 0, v4, vcc
	v_cmp_ne_u32_e32 vcc, 0, v27
	s_nop 1
	v_addc_co_u32_e32 v4, vcc, 0, v4, vcc
	v_cmp_ne_u32_e32 vcc, 0, v28
	s_nop 1
	v_addc_co_u32_e32 v4, vcc, 0, v4, vcc
	v_cmp_ne_u32_e32 vcc, 0, v29
	s_nop 1
	v_addc_co_u32_e32 v4, vcc, 0, v4, vcc
	v_cmp_ne_u32_e32 vcc, 0, v30
	s_nop 1
	v_addc_co_u32_e32 v4, vcc, 0, v4, vcc
	v_cmp_ne_u32_e32 vcc, 0, v31
	s_nop 1
	v_addc_co_u32_e32 v4, vcc, 0, v4, vcc
	global_load_dword v3, v7, s[4:5] sc1
	v_mov_b32_e32 v14, 0
	s_waitcnt vmcnt(0)
	v_max_u32_e32 v3, 1, v3
	v_max_u32_e32 v4, 1, v4
	ds_write_b32 v0, v3
	ds_write_b32 v0, v4 offset:4
.Lhb_have_1:
	buffer_inv sc1
	global_atomic_add v9, v6, v8, s[4:5] sc0
	v_add_u32_e32 v10, 1, v5
	v_mul_lo_u32 v11, v10, v3
	v_mul_lo_u32 v12, v10, v4
	s_waitcnt vmcnt(0)
	v_add_u32_e32 v9, 1, v9
	v_cmp_eq_u32_e32 vcc, v9, v11
	s_cbranch_vccz .Lhb_poll_1
	buffer_wbl2 sc1
	s_waitcnt vmcnt(0)
	global_atomic_add v13, v8, s[4:5]
.Lhb_poll_1:
	global_load_dword v9, v13, s[4:5] sc1
	s_waitcnt vmcnt(0)
	v_cmp_ge_u32_e32 vcc, v9, v12
	s_cbranch_vccnz .Lhb_done_1
	v_add_u32_e32 v14, 1, v14
	s_sleep 1
	v_cmp_gt_u32_e32 vcc, 0x8000, v14
	s_cbranch_vccnz .Lhb_poll_1
.Lhb_done_1:
	ds_write_b32 v0, v10 offset:8
	v_readlane_b32 s4, v2, 1
	v_readlane_b32 s5, v2, 2
	v_readlane_b32 s6, v2, 3
	v_readlane_b32 s7, v2, 4
	s_waitcnt vmcnt(0) lgkmcnt(0)
	s_nop 4

.LBB0_145:
	s_or_b64 exec, exec, s[2:3]
	s_mov_b32 s2, s91
	s_mov_b32 s4, 0
	s_waitcnt vmcnt(0)
	s_mov_b32 s5, 0
	v_or_b32_e32 v0, s2, v230
	v_cmp_eq_u32_e32 vcc, 0, v0
	s_waitcnt lgkmcnt(0)
	s_barrier
	s_and_saveexec_b64 s[2:3], vcc
	s_cbranch_execz .LBB0_189
	v_writelane_b32 v2, s4, 1
	v_writelane_b32 v2, s5, 2
	v_writelane_b32 v2, s6, 3
	v_writelane_b32 v2, s7, 4
	v_readlane_b32 s4, v251, 0
	v_readlane_b32 s5, v251, 1
	s_getreg_b32 s6, hwreg(HW_REG_XCC_ID, 0, 4)
	s_load_dword s7, s[4:5], 0x100
	s_load_dwordx2 s[4:5], s[4:5], 0xf0
	v_mov_b32_e32 v0, 0x20010
	ds_read_b32 v3, v0
	ds_read_b32 v4, v0 offset:4
	ds_read_b32 v5, v0 offset:8
	s_and_b32 s6, s6, 15
	s_lshl_b32 s6, s6, 8
	v_mov_b32_e32 v13, 0x3400
	v_mov_b32_e32 v8, 1
	v_mov_b32_e32 v14, 0
	s_waitcnt lgkmcnt(0)
	s_add_u32 s4, s4, 0xee42000
	s_addc_u32 s5, s5, 0
	v_mov_b32_e32 v6, s6
	v_add_u32_e32 v7, 0x400, v6
	v_add_u32_e32 v6, 0x1400, v6
	buffer_inv sc1
	global_atomic_add v9, v6, v8, s[4:5] sc0
	v_add_u32_e32 v10, 1, v5
	v_mul_lo_u32 v11, v10, v3
	v_mul_lo_u32 v12, v10, v4
	s_waitcnt vmcnt(0)
	v_add_u32_e32 v9, 1, v9
	v_cmp_eq_u32_e32 vcc, v9, v11
	s_cbranch_vccz .Lhb_poll_2
	buffer_wbl2 sc1
	s_waitcnt vmcnt(0)
	global_atomic_add v13, v8, s[4:5]

.LBB0_189:
	s_or_b64 exec, exec, s[2:3]
	s_cmpk_lt_i32 s90, 0x1e0
	v_readlane_b32 s16, v251, 0
	s_cselect_b64 s[0:1], -1, 0
	v_readlane_b32 s17, v251, 1
	v_writelane_b32 v251, s0, 2
	s_ashr_i32 s74, s90, 31
	s_lshl_b32 s5, s90, 4
	v_writelane_b32 v251, s1, 3
	s_add_i32 s0, s90, 0x7fe20
	s_and_b32 s1, s90, 7
	s_lshr_b32 s0, s0, 3
	s_mul_i32 s1, s1, 48
	s_add_i32 s2, s1, s0
	s_and_b32 s0, s2, 0xffff
	s_mul_i32 s0, s0, 0xaaab
	s_lshr_b32 s3, s0, 22
	s_lshl_b32 s0, s3, 3
	s_mulk_i32 s3, 0x60
	s_sub_i32 s2, s2, s3
	s_lshr_b32 s3, s74, 29
	s_add_i32 s3, s90, s3
	s_and_b32 s0, s0, 0xfff8
	s_ashr_i32 s7, s3, 3
	s_and_b32 s3, s3, -8
	v_writelane_b32 v251, s1, 4
	s_sub_i32 s1, 32, s0
	s_sub_i32 s8, s90, s3
	s_ashr_i32 s9, s90, 7
	s_bfe_u32 s4, s90, 0x40003
	s_lshl_b32 s3, s90, 2
	s_and_b32 s5, s5, 16
	s_min_u32 s1, s1, 8
	s_and_b32 s15, s90, 0x7f
	s_and_b32 s3, s3, 24
	s_or_b32 s6, s5, s4
	s_lshl_b32 s5, s9, 5
	s_lshl_b32 s4, s9, 2
	s_cmpk_lt_i32 s90, 0x80
	s_cselect_b64 s[76:77], -1, 0
	s_cmpk_gt_u32 s90, 0x7f
	s_cselect_b64 s[10:11], -1, 0
	v_writelane_b32 v251, s10, 5
	s_load_dwordx16 s[36:51], s[16:17], 0x98
	s_load_dwordx16 s[52:67], s[16:17], 0x58
	v_writelane_b32 v251, s11, 6
	s_mul_i32 s10, s90, 5
	s_add_i32 s11, s10, 0xfffffd80
	s_add_i32 s12, s10, 0xfffffd85
	s_cmp_lt_i32 s11, s12
	v_writelane_b32 v251, s12, 7
	s_cselect_b64 s[12:13], -1, 0
	v_writelane_b32 v251, s12, 8
	s_cmpk_gt_i32 s11, 0x1ff
	v_and_b32_e32 v1, 64, v230
	v_writelane_b32 v251, s13, 9
	s_cselect_b64 s[12:13], -1, 0
	v_writelane_b32 v251, s12, 10
	v_xor_b32_e32 v0, 32, v230
	v_add_u32_e32 v5, 64, v1
	v_writelane_b32 v251, s13, 11
	s_add_i32 s12, s10, 0xfffffb80
	s_cmpk_gt_u32 s12, 0xef
	s_cselect_b64 s[18:19], -1, 0
	v_writelane_b32 v251, s18, 12
	s_cmpk_gt_u32 s12, 0x1af
	v_cmp_lt_i32_e32 vcc, v0, v5
	v_writelane_b32 v251, s19, 13
	s_cselect_b64 s[18:19], -1, 0
	v_writelane_b32 v251, s18, 14
	s_cmpk_gt_u32 s12, 0x1cf
	v_xor_b32_e32 v1, 8, v230
	v_writelane_b32 v251, s19, 15
	s_cselect_b64 s[18:19], -1, 0
	v_writelane_b32 v251, s18, 16
	s_cmpk_gt_u32 s12, 0x1ef
	v_cndmask_b32_e32 v0, v230, v0, vcc
	v_writelane_b32 v251, s19, 17
	s_cselect_b64 s[18:19], -1, 0
	v_writelane_b32 v251, s18, 18
	s_cmpk_gt_u32 s12, 0x20f
	v_cmp_lt_i32_e32 vcc, v1, v5
	v_writelane_b32 v251, s19, 19
	s_cselect_b64 s[18:19], -1, 0
	v_writelane_b32 v251, s18, 20
	s_cmpk_gt_u32 s12, 0x24f
	v_xor_b32_e32 v2, 4, v230
	v_writelane_b32 v251, s19, 21
	s_cselect_b64 s[18:19], -1, 0
	v_writelane_b32 v251, s18, 22
	s_cmpk_gt_u32 s12, 0x34f
	v_cndmask_b32_e32 v1, v230, v1, vcc
	v_writelane_b32 v251, s19, 23
	v_writelane_b32 v251, s12, 24
	s_cselect_b64 s[12:13], -1, 0
	v_writelane_b32 v251, s12, 25
	v_cmp_lt_i32_e32 vcc, v2, v5
	v_xor_b32_e32 v3, 2, v230
	v_writelane_b32 v251, s13, 26
	s_add_i32 s12, s10, 0xfffff830
	v_writelane_b32 v251, s12, 27
	s_waitcnt lgkmcnt(0)
	s_add_u32 s12, s50, 0x1000000
	s_addc_u32 s13, s51, 0
	v_writelane_b32 v251, s12, 28
	v_cndmask_b32_e32 v2, v230, v2, vcc
	v_cmp_lt_i32_e32 vcc, v3, v5
	v_writelane_b32 v251, s13, 29
	s_add_i32 s13, s10, 0xfffff930
	s_add_u32 s18, s48, 0x1000000
	s_addc_u32 s19, s49, 0
	v_writelane_b32 v251, s18, 30
	s_add_i32 s12, s10, 0xfffff970
	v_xor_b32_e32 v4, 1, v230
	v_writelane_b32 v251, s19, 31
	s_add_u32 s18, s42, 0x400000
	v_writelane_b32 v251, s12, 32
	s_addc_u32 s19, s43, 0
	v_writelane_b32 v251, s18, 33
	s_add_i32 s12, s10, 0xfffff990
	v_cndmask_b32_e32 v3, v230, v3, vcc
	v_writelane_b32 v251, s19, 34
	s_add_u32 s18, s36, 0x200000
	v_writelane_b32 v251, s12, 35
	s_addc_u32 s19, s37, 0
	v_writelane_b32 v251, s18, 36
	s_add_i32 s12, s10, 0xfffff9b0
	v_cmp_lt_i32_e32 vcc, v4, v5
	v_writelane_b32 v251, s19, 37
	s_add_u32 s18, s66, 0x200000
	v_writelane_b32 v251, s12, 38
	s_addc_u32 s19, s67, 0
	v_writelane_b32 v251, s18, 39
	s_add_i32 s12, s10, 0xfffff9d0
	v_xor_b32_e32 v6, 16, v230
	v_writelane_b32 v251, s19, 40
	s_add_u32 s18, s64, 0x200000
	v_writelane_b32 v251, s12, 41
	s_addc_u32 s19, s65, 0
	v_writelane_b32 v251, s18, 42
	s_add_i32 s14, s10, 0xfffffa90
	v_cndmask_b32_e32 v4, v230, v4, vcc
	v_writelane_b32 v251, s19, 43
	s_add_u32 s18, s38, 0xc00000
	v_writelane_b32 v251, s36, 44
	s_addc_u32 s19, s39, 0
	v_cmp_lt_i32_e32 vcc, v6, v5
	v_writelane_b32 v251, s37, 45
	v_writelane_b32 v251, s38, 46
	v_writelane_b32 v251, s39, 47
	v_writelane_b32 v251, s40, 48
	v_writelane_b32 v251, s41, 49
	v_writelane_b32 v251, s42, 50
	v_writelane_b32 v251, s43, 51
	v_writelane_b32 v251, s44, 52
	v_writelane_b32 v251, s45, 53
	v_writelane_b32 v251, s46, 54
	v_writelane_b32 v251, s47, 55
	v_writelane_b32 v251, s48, 56
	v_writelane_b32 v251, s49, 57
	v_writelane_b32 v251, s50, 58
	v_writelane_b32 v251, s51, 59
	v_writelane_b32 v251, s18, 60
	v_cndmask_b32_e32 v5, v230, v6, vcc
	v_cvt_f32_ubyte0_e32 v6, s1
	v_writelane_b32 v251, s19, 61
	s_add_u32 s18, s52, 0xf00000
	v_writelane_b32 v251, s52, 62
	s_addc_u32 s19, s53, 0
	s_sub_i32 s12, s10, 48
	v_writelane_b32 v252, s54, 0
	v_writelane_b32 v252, s55, 1
	v_writelane_b32 v252, s56, 2
	v_writelane_b32 v252, s57, 3
	v_writelane_b32 v252, s58, 4
	v_writelane_b32 v252, s59, 5
	v_writelane_b32 v252, s60, 6
	v_writelane_b32 v252, s61, 7
	v_writelane_b32 v252, s62, 8
	v_writelane_b32 v252, s63, 9
	v_writelane_b32 v252, s64, 10
	v_writelane_b32 v252, s65, 11
	v_writelane_b32 v252, s66, 12
	v_writelane_b32 v252, s67, 13
	v_writelane_b32 v252, s18, 14
	s_cmpk_gt_i32 s11, 0xfe9f
	s_load_dwordx8 s[56:63], s[16:17], 0xd8
	v_writelane_b32 v252, s19, 15
	s_cselect_b64 s[18:19], -1, 0
	v_writelane_b32 v252, s18, 16
	s_cmpk_gt_u32 s12, 0x1af
	v_rcp_iflag_f32_e32 v7, v6
	v_writelane_b32 v252, s19, 17
	s_cselect_b64 s[18:19], -1, 0
	v_writelane_b32 v252, s18, 18
	s_cmpk_gt_u32 s12, 0x1cf
	v_cvt_f32_ubyte0_e32 v8, s2
	v_writelane_b32 v252, s19, 19
	s_cselect_b64 s[18:19], -1, 0
	v_writelane_b32 v252, s18, 20
	s_cmpk_gt_u32 s12, 0x1ef
	v_mul_f32_e32 v7, v8, v7
	v_writelane_b32 v252, s19, 21
	s_cselect_b64 s[18:19], -1, 0
	v_writelane_b32 v252, s18, 22
	s_cmpk_gt_u32 s12, 0x20f
	v_trunc_f32_e32 v7, v7
	v_writelane_b32 v252, s19, 23
	s_cselect_b64 s[18:19], -1, 0
	v_writelane_b32 v252, s18, 24
	s_cmp_lt_u32 s11, 0xfffffdb0
	v_fma_f32 v8, -v7, v6, v8
	v_writelane_b32 v252, s19, 25
	v_writelane_b32 v252, s11, 26
	s_cselect_b64 s[18:19], -1, 0
	v_writelane_b32 v252, s18, 27
	s_cmpk_gt_u32 s12, 0x34f
	v_cvt_u32_f32_e32 v7, v7
	v_writelane_b32 v252, s19, 28
	v_writelane_b32 v252, s12, 29
	s_cselect_b64 s[18:19], -1, 0
	v_writelane_b32 v252, s18, 30
	s_add_i32 s11, s10, 0xfffffdc0
	s_mov_b32 s65, 0
	v_writelane_b32 v252, s19, 31
	v_writelane_b32 v252, s11, 32
	s_add_i32 s11, s10, 0xfffffde0
	v_writelane_b32 v252, s11, 33
	s_add_i32 s11, s10, 0xfffffe00
	s_add_i32 s18, s10, 0xfffffc80
	v_writelane_b32 v252, s11, 34
	s_add_i32 s11, s10, 0xfffffe20
	s_add_i32 s19, s10, 0xfffffee0
	v_writelane_b32 v252, s11, 35
	s_waitcnt lgkmcnt(0)
	s_add_u32 s10, s60, 0x1000000
	v_writelane_b32 v252, s10, 36
	s_addc_u32 s10, s61, 0
	v_writelane_b32 v252, s10, 37
	s_lshl_b32 s10, s90, 3
	s_add_i32 s11, s10, 0xfffffe88
	s_min_i32 s11, s11, 0x650
	s_lshl_b32 s12, s8, 4
	s_ashr_i32 s75, s72, 31
	s_add_i32 s20, s10, 0xfffffe80
	s_cmp_lt_i32 s20, s11
	v_writelane_b32 v252, s11, 38
	s_cselect_b64 s[22:23], -1, 0
	v_writelane_b32 v252, s22, 39
	s_cmpk_gt_i32 s20, 0x1ff
	s_mul_i32 s11, s90, 3
	v_writelane_b32 v252, s23, 40
	s_cselect_b64 s[22:23], -1, 0
	v_writelane_b32 v252, s22, 41
	v_writelane_b32 v251, s53, 63
	v_lshlrev_b32_e32 v231, 2, v0
	v_writelane_b32 v252, s23, 42
	v_writelane_b32 v252, s18, 43
	s_add_i32 s18, s18, s11
	s_cmpk_gt_u32 s18, 0xef
	s_cselect_b64 s[22:23], -1, 0
	v_writelane_b32 v252, s22, 44
	s_cmpk_gt_u32 s18, 0x1af
	v_lshlrev_b32_e32 v232, 2, v1
	v_writelane_b32 v252, s23, 45
	s_cselect_b64 s[22:23], -1, 0
	v_writelane_b32 v252, s22, 46
	s_cmpk_gt_u32 s18, 0x1cf
	v_lshlrev_b32_e32 v233, 2, v2
	v_writelane_b32 v252, s23, 47
	s_cselect_b64 s[22:23], -1, 0
	v_writelane_b32 v252, s22, 48
	s_cmpk_gt_u32 s18, 0x1ef
	v_lshlrev_b32_e32 v234, 2, v3
	v_writelane_b32 v252, s23, 49
	s_cselect_b64 s[22:23], -1, 0
	v_writelane_b32 v252, s22, 50
	s_cmpk_gt_u32 s18, 0x20f
	v_lshlrev_b32_e32 v235, 2, v4
	v_writelane_b32 v252, s23, 51
	s_cselect_b64 s[22:23], -1, 0
	v_writelane_b32 v252, s22, 52
	s_cmpk_gt_u32 s18, 0x24f
	v_lshlrev_b32_e32 v236, 2, v5
	v_writelane_b32 v252, s23, 53
	s_cselect_b64 s[22:23], -1, 0
	v_writelane_b32 v252, s22, 54
	s_cmpk_gt_u32 s18, 0x34f
	v_mov_b32_e32 v1, 0
	v_writelane_b32 v252, s23, 55
	v_writelane_b32 v252, s18, 56
	s_cselect_b64 s[22:23], -1, 0
	v_writelane_b32 v252, s22, 57
	v_mov_b32_e32 v237, 1
	v_mov_b32_e32 v238, 0x3727c5ac
	v_writelane_b32 v252, s23, 58
	v_writelane_b32 v252, s13, 59
	s_add_i32 s13, s13, s11
	v_writelane_b32 v252, s13, 60
	s_add_i32 s13, s10, 0xfffffa30
	v_writelane_b32 v252, s13, 61
	s_add_i32 s13, s10, 0xfffffa70
	v_writelane_b32 v252, s13, 62
	s_add_i32 s13, s14, s11
	v_writelane_b32 v253, s13, 0
	s_add_i32 s13, s10, 0xfffffab0
	v_writelane_b32 v253, s13, 1
	s_add_i32 s13, s10, 0xfffffad0
	v_writelane_b32 v253, s13, 2
	s_add_i32 s13, s10, 0xfffffb90
	v_writelane_b32 v253, s13, 3
	s_add_i32 s13, s10, 0xd0
	s_cmpk_gt_i32 s20, 0xfe9f
	s_cselect_b64 s[22:23], -1, 0
	v_writelane_b32 v253, s22, 4
	s_cmpk_gt_u32 s13, 0x1af
	v_writelane_b32 v252, s14, 63
	v_writelane_b32 v253, s23, 5
	s_cselect_b64 s[22:23], -1, 0
	v_writelane_b32 v253, s22, 6
	s_cmpk_gt_u32 s13, 0x1cf
	v_mov_b32_e32 v239, 0x3e000000
	v_writelane_b32 v253, s23, 7
	s_cselect_b64 s[22:23], -1, 0
	v_writelane_b32 v253, s22, 8
	s_cmpk_gt_u32 s13, 0x1ef
	v_mov_b32_e32 v240, 0x6050400
	v_writelane_b32 v253, s23, 9
	s_cselect_b64 s[22:23], -1, 0
	v_writelane_b32 v253, s22, 10
	s_cmpk_gt_u32 s13, 0x20f
	v_mov_b32_e32 v242, 0xf149f2ca
	v_writelane_b32 v253, s23, 11
	s_cselect_b64 s[22:23], -1, 0
	v_writelane_b32 v253, s22, 12
	s_cmp_lt_u32 s20, 0xfffffdb0
	v_mov_b32_e32 v243, 0x7f800000
	v_writelane_b32 v253, s23, 13
	v_writelane_b32 v253, s20, 14
	s_cselect_b64 s[20:21], -1, 0
	v_writelane_b32 v253, s20, 15
	s_cmpk_gt_u32 s13, 0x34f
	v_mov_b32_e32 v244, 0x42000000
	v_writelane_b32 v253, s21, 16
	v_writelane_b32 v253, s13, 17
	s_cselect_b64 s[20:21], -1, 0
	v_writelane_b32 v253, s20, 18
	s_add_i32 s11, s19, s11
	v_mov_b32_e32 v245, 0x42800000
	v_writelane_b32 v253, s21, 19
	v_writelane_b32 v253, s19, 20
	v_writelane_b32 v253, s11, 21
	s_add_i32 s11, s10, 0xfffffd80
	v_writelane_b32 v253, s11, 22
	s_add_i32 s11, s10, 0xfffffec0
	v_writelane_b32 v253, s11, 23
	s_add_i32 s11, s10, 0xffffff00
	v_writelane_b32 v253, s11, 24
	s_add_i32 s11, s10, 0xffffff20
	s_sub_i32 s10, s10, 32
	v_writelane_b32 v253, s11, 25
	s_cmpk_lt_i32 s90, 0x200
	v_writelane_b32 v253, s10, 26
	s_cselect_b64 s[10:11], -1, 0
	v_writelane_b32 v253, s10, 27
	v_not_b32_e32 v246, 63
	v_mov_b64_e32 v[198:199], 0x200
	v_writelane_b32 v253, s11, 28
	s_lshl_b32 s10, s9, 11
	s_ashr_i32 s11, s10, 31
	s_lshl_b64 s[18:19], s[10:11], 1
	s_lshl_b32 s9, s8, 6
	s_cmpk_lt_u32 s90, 0x80
	s_mov_b32 s10, 0xc23e000
	s_cselect_b32 s10, s10, 0x5a3e000
	s_cmp_lt_i32 s8, 0
	s_cselect_b32 s11, 61, 60
	v_writelane_b32 v253, s10, 29
	s_mul_i32 s10, s8, 17
	s_mul_i32 s11, s8, s11
	s_mulk_i32 s8, 0x41
	s_cselect_b32 s10, s10, s12
	s_cselect_b32 s8, s8, s9
	s_add_i32 s11, s11, s7
	s_mul_hi_i32 s9, s11, 0x88888889
	s_add_i32 s9, s9, s11
	s_lshr_b32 s12, s9, 31
	s_ashr_i32 s9, s9, 6
	s_add_i32 s9, s9, s12
	s_mul_i32 s12, s9, 0x78
	s_sub_i32 s11, s11, s12
	s_bfe_i32 s12, s11, 0x80000
	s_bfe_u32 s12, s12, 0x3000c
	s_add_i32 s12, s11, s12
	s_and_b32 s13, s12, 0xf8
	s_sub_i32 s11, s11, s13
	s_lshl_b32 s9, s9, 3
	s_sext_i32_i8 s11, s11
	s_add_i32 s9, s9, s11
	v_writelane_b32 v253, s9, 30
	s_add_i32 s9, s10, s7
	s_ashr_i32 s10, s9, 31
	s_lshr_b32 s10, s10, 27
	s_add_i32 s10, s9, s10
	s_and_b32 s11, s10, 0xffe0
	s_sub_i32 s9, s9, s11
	s_bfe_i32 s11, s9, 0x80000
	s_add_i32 s7, s8, s7
	s_bfe_u32 s11, s11, 0x3000c
	s_ashr_i32 s8, s7, 31
	s_add_i32 s11, s9, s11
	s_lshr_b32 s8, s8, 25
	s_and_b32 s13, s11, 0xf8
	s_add_i32 s8, s7, s8
	s_sub_i32 s9, s9, s13
	s_and_b32 s13, s8, 0xff80
	s_sub_i32 s7, s7, s13
	s_bfe_i32 s12, s12, 0x80000
	s_bfe_i32 s13, s7, 0x80000
	s_sext_i32_i16 s12, s12
	s_bfe_u32 s13, s13, 0x3000c
	s_ashr_i32 s12, s12, 3
	s_add_i32 s13, s7, s13
	v_writelane_b32 v253, s12, 31
	s_bfe_u32 s12, s15, 0x30003
	s_and_b32 s14, s13, 0xf8
	s_lshr_b32 s6, s6, 3
	s_or_b32 s3, s12, s3
	s_sub_i32 s7, s7, s14
	s_or_b32 s14, s3, s5
	s_or_b32 s20, s4, s6
	s_ashr_i32 s4, s10, 5
	s_bfe_i32 s5, s11, 0x80000
	s_lshl_b32 s4, s4, 3
	s_sext_i32_i16 s10, s5
	s_sext_i32_i8 s5, s9
	s_add_i32 s22, s4, s5
	s_ashr_i32 s4, s8, 7
	s_bfe_i32 s5, s13, 0x80000
	s_lshl_b32 s4, s4, 3
	s_sext_i32_i16 s5, s5
	s_sext_i32_i8 s7, s7
	v_writelane_b32 v253, s15, 32
	s_add_i32 s8, s4, s7
	s_ashr_i32 s4, s5, 3
	v_writelane_b32 v253, s4, 33
	s_lshr_b32 s4, s5, 3
	s_bfe_i64 s[4:5], s[4:5], 0x100000
	s_lshl_b64 s[4:5], s[4:5], 19
	v_writelane_b32 v253, s4, 34
	s_or_b32 s78, s3, 64
	s_or_b32 s79, s6, 8
	v_writelane_b32 v253, s5, 35
	s_lshl_b32 s4, s3, 21
	v_writelane_b32 v253, s4, 36
	s_lshl_b32 s4, s6, 21
	v_writelane_b32 v253, s4, 37
	s_lshl_b32 s4, s6, 8
	s_lshl_b32 s3, s3, 8
	v_writelane_b32 v253, s4, 38
	s_ashr_i32 s4, s10, 3
	v_writelane_b32 v253, s4, 39
	s_or_b32 s5, s3, 16
	v_writelane_b32 v253, s5, 40
	s_or_b32 s5, s3, 32
	v_writelane_b32 v253, s5, 41
	s_or_b32 s5, s3, 48
	v_writelane_b32 v253, s5, 42
	s_or_b32 s5, s3, 0x80
	v_writelane_b32 v253, s5, 43
	s_or_b32 s5, s3, 0x90
	v_writelane_b32 v253, s5, 44
	s_or_b32 s5, s3, 0xa0
	v_writelane_b32 v253, s5, 45
	v_writelane_b32 v253, s3, 46
	s_or_b32 s3, s3, 0xb0
	v_writelane_b32 v253, s3, 47
	s_mov_b32 s6, s14
	s_ashr_i32 s15, s14, 31
	v_writelane_b32 v253, s6, 48
	s_ashr_i32 s21, s20, 31
	s_ashr_i32 s9, s8, 31
	v_writelane_b32 v253, s7, 49
	s_lshl_b64 s[6:7], s[14:15], 18
	v_writelane_b32 v253, s6, 50
	s_lshr_b32 s4, s10, 3
	s_add_i32 s3, s90, 0xfffffca0
	v_writelane_b32 v253, s7, 51
	s_mov_b32 s6, s20
	v_writelane_b32 v253, s6, 52
	v_mov_b64_e32 v[200:201], 0x1ff
	s_mov_b32 s70, 0x5a3e000
	v_writelane_b32 v253, s7, 53
	s_lshl_b64 s[6:7], s[20:21], 18
	v_writelane_b32 v253, s6, 54
	s_movk_i32 s81, 0x2000
	s_mov_b32 s84, 0x12000
	v_writelane_b32 v253, s7, 55
	s_mov_b32 s6, s8
	v_writelane_b32 v253, s6, 56
	s_mov_b32 s85, 0x14000
	s_mov_b32 s88, 0x16000
	v_writelane_b32 v253, s7, 57
	s_lshl_b64 s[6:7], s[8:9], 19
	v_writelane_b32 v253, s6, 58
	s_cmp_gt_u32 s3, 0xfffffe7f
	v_readfirstlane_b32 s3, v7
	v_writelane_b32 v253, s7, 59
	s_cselect_b64 s[6:7], -1, 0
	v_writelane_b32 v253, s6, 60
	s_bfe_i64 s[4:5], s[4:5], 0x100000
	s_lshl_b64 s[4:5], s[4:5], 19
	v_writelane_b32 v253, s7, 61
	v_writelane_b32 v253, s4, 62
	s_ashr_i32 s23, s22, 31
	s_movk_i32 s89, 0x4000
	v_writelane_b32 v253, s5, 63
	s_mov_b32 s4, s22
	v_writelane_b32 v254, s4, 0
	s_movk_i32 s92, 0x6000
	s_movk_i32 s93, 0x3000
	v_writelane_b32 v254, s5, 1
	s_lshl_b64 s[4:5], s[22:23], 19
	v_writelane_b32 v254, s4, 2
	s_mov_b32 s94, 0x18000
	s_mov_b32 s95, 0x1a000
	v_writelane_b32 v254, s5, 3
	v_cmp_ge_f32_e64 s[4:5], |v8|, v6
	s_cmp_lg_u64 s[4:5], 0
	s_addc_u32 s6, s3, 0
	s_mul_i32 s6, s6, s1
	s_sub_i32 s1, s2, s6
	s_and_b32 s1, s1, 0xff
	s_add_i32 s0, s1, s0
	s_cmp_lg_u64 s[4:5], 0
	v_writelane_b32 v254, s0, 4
	s_addc_u32 s0, s3, 15
	s_abs_i32 s1, s72
	v_cvt_f32_u32_e32 v6, s1
	s_sub_i32 s2, 0, s1
	s_and_b32 s0, s0, 0xff
	v_writelane_b32 v254, s0, 5
	v_rcp_iflag_f32_e32 v6, v6
	s_mov_b32 s96, 0x8000
	s_mov_b32 s97, 0xa000
	s_mov_b32 s69, 0x1c000
	v_mul_f32_e32 v6, 0x4f7ffffe, v6
	v_cvt_u32_f32_e32 v6, v6
	s_mov_b32 s68, 0x1e000
	s_movk_i32 s66, 0x1e00
	s_mov_b32 s67, 0x800000
	v_readfirstlane_b32 s3, v6
	s_mul_i32 s2, s2, s3
	s_mul_hi_u32 s2, s3, s2
	s_add_i32 s3, s3, s2
	s_lshr_b32 s0, s3, 19
	s_mul_i32 s2, s0, s1
	s_sub_i32 s2, 0x2000, s2
	s_add_i32 s3, s0, 1
	s_sub_i32 s4, s2, s1
	s_cmp_ge_u32 s2, s1
	s_cselect_b32 s0, s3, s0
	s_cselect_b32 s2, s4, s2
	s_add_i32 s3, s0, 1
	s_cmp_ge_u32 s2, s1
	s_mul_i32 s1, s73, s72
	s_cselect_b32 s0, s3, s0
	s_mul_i32 s73, s1, s33
	s_lshl_b32 s1, s90, 23
	s_xor_b32 s0, s0, s75
	s_and_b32 s1, s1, 0x3000000
	s_lshl_b32 s2, s12, 21
	s_sub_i32 s0, s0, s75
	s_or_b32 s1, s1, s2
	s_mul_i32 s2, s0, s90
	s_ashr_i32 s3, s2, 31
	s_add_i32 s80, s2, s0
	v_writelane_b32 v254, s2, 6
	s_add_i32 s0, s2, 1
	s_mov_b32 s33, 0x3fb8aa3b
	v_writelane_b32 v254, s3, 7
	v_writelane_b32 v254, s0, 8
	s_add_u32 s0, s18, s1
	v_writelane_b32 v254, s18, 9
	s_addc_u32 s1, s19, 0
	s_add_u32 s0, s0, 0x833e080
	v_writelane_b32 v254, s19, 10
	v_writelane_b32 v254, s0, 11
	s_addc_u32 s0, s1, 0
	v_writelane_b32 v254, s0, 12
	s_add_i32 s0, 0, 0x20010
	v_writelane_b32 v254, s0, 13
	s_add_i32 s0, 0, 0x20014
	v_writelane_b32 v254, s0, 14
	s_add_i32 s0, 0, 0x20000
	v_writelane_b32 v254, s0, 15
	s_mov_b64 s[0:1], -1
	v_writelane_b32 v254, s0, 16
	s_mov_b64 s[86:87], 0x80
	s_mov_b32 s4, s65
	v_writelane_b32 v254, s1, 17
	s_load_dwordx2 s[0:1], s[16:17], 0x38
	s_waitcnt lgkmcnt(0)
	s_barrier
	v_writelane_b32 v254, s0, 18
	s_nop 1
	v_writelane_b32 v254, s1, 19
	s_load_dwordx4 s[0:3], s[16:17], 0x0
	s_waitcnt lgkmcnt(0)
	v_writelane_b32 v254, s0, 20
	s_nop 1
	v_writelane_b32 v254, s1, 21
	v_writelane_b32 v254, s2, 22
	v_writelane_b32 v254, s3, 23
	s_mov_b32 s2, 0x20000
	v_writelane_b32 v254, s0, 24
	s_nop 1
	v_writelane_b32 v254, s1, 25
	v_writelane_b32 v254, s2, 26
	v_writelane_b32 v254, s3, 27
	s_mov_b32 s2, 0x40000
	v_writelane_b32 v254, s0, 28
	s_nop 1
	v_writelane_b32 v254, s1, 29
	v_writelane_b32 v254, s2, 30
	v_writelane_b32 v254, s3, 31
	v_writelane_b32 v254, s90, 32
	s_mov_b32 s0, s72
	v_writelane_b32 v254, s0, 33
	s_nop 1
	v_writelane_b32 v254, s1, 34
	v_writelane_b32 v254, s91, 35
	v_writelane_b32 v254, s74, 36
	v_writelane_b32 v254, s76, 37
	s_nop 1
	v_writelane_b32 v254, s77, 38
	v_writelane_b32 v254, s56, 39
	s_nop 1
	v_writelane_b32 v254, s57, 40
	v_writelane_b32 v254, s58, 41
	v_writelane_b32 v254, s59, 42
	v_writelane_b32 v254, s60, 43
	v_writelane_b32 v254, s61, 44
	v_writelane_b32 v254, s62, 45
	v_writelane_b32 v254, s63, 46
	v_writelane_b32 v254, s75, 47
	v_writelane_b32 v254, s78, 48
	v_writelane_b32 v254, s79, 49
	v_writelane_b32 v254, s73, 50
	v_writelane_b32 v254, s80, 51
	s_branch .LBB0_192
.LBB0_191:
	s_or_b64 exec, exec, s[0:1]
	s_mov_b64 s[0:1], 0
	v_writelane_b32 v254, s0, 16
	s_mov_b32 s4, 1
	s_waitcnt lgkmcnt(0)
	v_writelane_b32 v254, s1, 17
	s_barrier
	v_readlane_b32 s0, v254, 55
	v_readlane_b32 s1, v254, 56
	s_and_b64 vcc, exec, s[0:1]
	s_cbranch_vccz .LBB0_192
	s_getpc_b64 s[98:99]

.LBB0_314:
	s_mov_b32 s0, s91
	s_mov_b32 s64, 0
	s_waitcnt vmcnt(0)
	s_waitcnt vmcnt(0) lgkmcnt(0)
	v_or_b32_e32 v0, s0, v230
	v_cmp_eq_u32_e32 vcc, 0, v0
	s_barrier
	s_and_saveexec_b64 s[0:1], vcc
	s_cbranch_execz .LBB0_358
	v_writelane_b32 v2, s4, 1
	v_writelane_b32 v2, s5, 2
	v_writelane_b32 v2, s6, 3
	v_writelane_b32 v2, s7, 4
	v_readlane_b32 s4, v251, 0
	v_readlane_b32 s5, v251, 1
	s_getreg_b32 s6, hwreg(HW_REG_XCC_ID, 0, 4)
	s_load_dword s7, s[4:5], 0x100
	s_load_dwordx2 s[4:5], s[4:5], 0xf0
	v_mov_b32_e32 v0, 0x20010
	ds_read_b32 v3, v0
	ds_read_b32 v4, v0 offset:4
	ds_read_b32 v5, v0 offset:8
	s_and_b32 s6, s6, 15
	s_lshl_b32 s6, s6, 8
	v_mov_b32_e32 v13, 0x3400
	v_mov_b32_e32 v8, 1
	v_mov_b32_e32 v14, 0
	s_waitcnt lgkmcnt(0)
	s_add_u32 s4, s4, 0xee42000
	s_addc_u32 s5, s5, 0
	v_mov_b32_e32 v6, s6
	v_add_u32_e32 v7, 0x400, v6
	v_add_u32_e32 v6, 0x1400, v6
	buffer_inv sc1
	global_atomic_add v9, v6, v8, s[4:5] sc0
	v_add_u32_e32 v10, 1, v5
	v_mul_lo_u32 v11, v10, v3
	v_mul_lo_u32 v12, v10, v4
	s_waitcnt vmcnt(0)
	v_add_u32_e32 v9, 1, v9
	v_cmp_eq_u32_e32 vcc, v9, v11
	s_cbranch_vccz .Lhb_poll_3
	buffer_wbl2 sc1
	s_waitcnt vmcnt(0)
	global_atomic_add v13, v8, s[4:5]

.LBB0_555:
	s_mov_b32 s0, s91
	s_mov_b32 s64, 0
	s_waitcnt vmcnt(0)
	s_waitcnt lgkmcnt(0)
	v_or_b32_e32 v0, s0, v230
	v_cmp_eq_u32_e32 vcc, 0, v0
	s_barrier
	s_and_saveexec_b64 s[0:1], vcc
	s_mov_b32 s70, 0x10000
	s_cbranch_execz .LBB0_599
	v_writelane_b32 v2, s4, 1
	v_writelane_b32 v2, s5, 2
	v_writelane_b32 v2, s6, 3
	v_writelane_b32 v2, s7, 4
	v_readlane_b32 s4, v251, 0
	v_readlane_b32 s5, v251, 1
	s_getreg_b32 s6, hwreg(HW_REG_XCC_ID, 0, 4)
	s_load_dword s7, s[4:5], 0x100
	s_load_dwordx2 s[4:5], s[4:5], 0xf0
	v_mov_b32_e32 v0, 0x20010
	ds_read_b32 v3, v0
	ds_read_b32 v4, v0 offset:4
	ds_read_b32 v5, v0 offset:8
	s_and_b32 s6, s6, 15
	s_lshl_b32 s6, s6, 8
	v_mov_b32_e32 v13, 0x3400
	v_mov_b32_e32 v8, 1
	v_mov_b32_e32 v14, 0
	s_waitcnt lgkmcnt(0)
	s_add_u32 s4, s4, 0xee42000
	s_addc_u32 s5, s5, 0
	v_mov_b32_e32 v6, s6
	v_add_u32_e32 v7, 0x400, v6
	v_add_u32_e32 v6, 0x1400, v6
	buffer_inv sc1
	global_atomic_add v9, v6, v8, s[4:5] sc0
	v_add_u32_e32 v10, 1, v5
	v_mul_lo_u32 v11, v10, v3
	v_mul_lo_u32 v12, v10, v4
	s_waitcnt vmcnt(0)
	v_add_u32_e32 v9, 1, v9
	v_cmp_eq_u32_e32 vcc, v9, v11
	s_cbranch_vccz .Lhb_poll_4
	buffer_wbl2 sc1
	s_waitcnt vmcnt(0)
	global_atomic_add v13, v8, s[4:5]

.LBB0_760:
	s_mov_b32 s0, s91
	s_mov_b32 s70, 0
	s_waitcnt vmcnt(0)
	s_waitcnt lgkmcnt(0)
	v_or_b32_e32 v0, s0, v230
	v_cmp_eq_u32_e32 vcc, 0, v0
	s_barrier
	s_and_saveexec_b64 s[0:1], vcc
	s_cbranch_execz .LBB0_804
	v_writelane_b32 v2, s4, 1
	v_writelane_b32 v2, s5, 2
	v_writelane_b32 v2, s6, 3
	v_writelane_b32 v2, s7, 4
	v_readlane_b32 s4, v251, 0
	v_readlane_b32 s5, v251, 1
	s_getreg_b32 s6, hwreg(HW_REG_XCC_ID, 0, 4)
	s_load_dword s7, s[4:5], 0x100
	s_load_dwordx2 s[4:5], s[4:5], 0xf0
	v_mov_b32_e32 v0, 0x20010
	ds_read_b32 v3, v0
	ds_read_b32 v4, v0 offset:4
	ds_read_b32 v5, v0 offset:8
	s_and_b32 s6, s6, 15
	s_lshl_b32 s6, s6, 8
	v_mov_b32_e32 v13, 0x3400
	v_mov_b32_e32 v8, 1
	v_mov_b32_e32 v14, 0
	s_waitcnt lgkmcnt(0)
	s_add_u32 s4, s4, 0xee42000
	s_addc_u32 s5, s5, 0
	v_mov_b32_e32 v6, s6
	v_add_u32_e32 v7, 0x400, v6
	v_add_u32_e32 v6, 0x1400, v6
	buffer_inv sc1
	global_atomic_add v9, v6, v8, s[4:5] sc0
	v_add_u32_e32 v10, 1, v5
	v_mul_lo_u32 v11, v10, v3
	v_mul_lo_u32 v12, v10, v4
	s_waitcnt vmcnt(0)
	v_add_u32_e32 v9, 1, v9
	v_cmp_eq_u32_e32 vcc, v9, v11
	s_cbranch_vccz .Lhb_poll_5
	buffer_wbl2 sc1
	s_waitcnt vmcnt(0)
	global_atomic_add v13, v8, s[4:5]

.LBB0_1032:
	v_writelane_b32 v255, s82, 18
	s_nop 1
	v_writelane_b32 v255, s83, 19
	s_mov_b64 s[82:83], 0x20000
	s_or_b64 exec, exec, s[6:7]
	s_mov_b32 s0, s91
	s_mov_b32 s70, 0
	s_waitcnt vmcnt(0)
	s_waitcnt lgkmcnt(0)
	v_or_b32_e32 v0, s0, v230
	v_cmp_eq_u32_e32 vcc, 0, v0
	s_barrier
	s_and_saveexec_b64 s[0:1], vcc
	s_cbranch_execz .LBB0_1076
	v_writelane_b32 v2, s4, 1
	v_writelane_b32 v2, s5, 2
	v_writelane_b32 v2, s6, 3
	v_writelane_b32 v2, s7, 4
	v_readlane_b32 s4, v251, 0
	v_readlane_b32 s5, v251, 1
	s_getreg_b32 s6, hwreg(HW_REG_XCC_ID, 0, 4)
	s_load_dword s7, s[4:5], 0x100
	s_load_dwordx2 s[4:5], s[4:5], 0xf0
	v_mov_b32_e32 v0, 0x20010
	ds_read_b32 v3, v0
	ds_read_b32 v4, v0 offset:4
	ds_read_b32 v5, v0 offset:8
	s_and_b32 s6, s6, 15
	s_lshl_b32 s6, s6, 8
	v_mov_b32_e32 v13, 0x3400
	v_mov_b32_e32 v8, 1
	v_mov_b32_e32 v14, 0
	s_waitcnt lgkmcnt(0)
	s_add_u32 s4, s4, 0xee42000
	s_addc_u32 s5, s5, 0
	v_mov_b32_e32 v6, s6
	v_add_u32_e32 v7, 0x400, v6
	v_add_u32_e32 v6, 0x1400, v6
	buffer_inv sc1
	global_atomic_add v9, v6, v8, s[4:5] sc0
	v_add_u32_e32 v10, 1, v5
	v_mul_lo_u32 v11, v10, v3
	v_mul_lo_u32 v12, v10, v4
	s_waitcnt vmcnt(0)
	v_add_u32_e32 v9, 1, v9
	v_cmp_eq_u32_e32 vcc, v9, v11
	s_cbranch_vccz .Lhb_poll_7
	buffer_wbl2 sc1
	s_waitcnt vmcnt(0)
	global_atomic_add v13, v8, s[4:5]

.LBB0_1096:
	s_mov_b32 s0, s91
	s_mov_b32 s36, 0
	s_waitcnt vmcnt(0)
	s_waitcnt vmcnt(0) lgkmcnt(0)
	v_or_b32_e32 v0, s0, v230
	v_cmp_eq_u32_e32 vcc, 0, v0
	s_barrier
	s_and_saveexec_b64 s[0:1], vcc
	s_mov_b32 s70, 0x5a3e000
	s_cbranch_execz .LBB0_1140
	v_writelane_b32 v2, s4, 1
	v_writelane_b32 v2, s5, 2
	v_writelane_b32 v2, s6, 3
	v_writelane_b32 v2, s7, 4
	v_readlane_b32 s4, v251, 0
	v_readlane_b32 s5, v251, 1
	s_getreg_b32 s6, hwreg(HW_REG_XCC_ID, 0, 4)
	s_load_dword s7, s[4:5], 0x100
	s_load_dwordx2 s[4:5], s[4:5], 0xf0
	v_mov_b32_e32 v0, 0x20010
	ds_read_b32 v3, v0
	ds_read_b32 v4, v0 offset:4
	ds_read_b32 v5, v0 offset:8
	s_and_b32 s6, s6, 15
	s_lshl_b32 s6, s6, 8
	v_mov_b32_e32 v13, 0x3400
	v_mov_b32_e32 v8, 1
	v_mov_b32_e32 v14, 0
	s_waitcnt lgkmcnt(0)
	s_add_u32 s4, s4, 0xee42000
	s_addc_u32 s5, s5, 0
	v_mov_b32_e32 v6, s6
	v_add_u32_e32 v7, 0x400, v6
	v_add_u32_e32 v6, 0x1400, v6
	buffer_inv sc1
	global_atomic_add v9, v6, v8, s[4:5] sc0
	v_add_u32_e32 v10, 1, v5
	v_mul_lo_u32 v11, v10, v3
	v_mul_lo_u32 v12, v10, v4
	s_waitcnt vmcnt(0)
	v_add_u32_e32 v9, 1, v9
	v_cmp_eq_u32_e32 vcc, v9, v11
	s_cbranch_vccz .Lhb_poll_8
	buffer_wbl2 sc1
	s_waitcnt vmcnt(0)
	global_atomic_add v13, v8, s[4:5]

.LBB0_1146:
	v_mov_b32_e32 v0, v230
	s_mov_b32 s4, s91
	s_mov_b32 s65, s25
	s_mov_b32 s64, 0
	s_xor_b64 s[0:1], s[64:65], s[62:63]
	v_readlane_b32 s5, v253, 29
	s_add_u32 s0, s0, s5
	s_addc_u32 s1, s1, 0
	s_ashr_i32 s5, s4, 2
	s_andn2_b32 s5, s5, 63
	v_and_or_b32 v134, v0, 15, s5
	s_lshr_b32 s4, s4, 1
	v_readlane_b32 s5, v253, 46
	s_and_b32 s4, s4, 0x60
	v_ashrrev_i32_e32 v0, 1, v0
	v_add_u32_e32 v130, s5, v134
	v_readlane_b32 s5, v253, 38
	v_and_b32_e32 v0, -8, v0
	s_add_i32 s4, s4, s5
	v_add_u32_e32 v132, s4, v0
	v_readlane_b32 s4, v253, 40
	v_cvt_pk_bf16_f32 v110, v110, v111
	v_cvt_pk_bf16_f32 v111, v112, v113
	v_cvt_pk_bf16_f32 v112, v106, v107
	v_add_u32_e32 v106, s4, v134
	v_readlane_b32 s4, v253, 41
	v_cvt_pk_bf16_f32 v94, v94, v95
	v_cvt_pk_bf16_f32 v95, v96, v97
	v_cvt_pk_bf16_f32 v96, v90, v91
	v_add_u32_e32 v90, s4, v134
	v_readlane_b32 s4, v253, 42
	v_cvt_pk_bf16_f32 v78, v78, v79
	v_cvt_pk_bf16_f32 v79, v80, v81
	v_cvt_pk_bf16_f32 v80, v74, v75
	v_add_u32_e32 v74, s4, v134
	v_readlane_b32 s4, v253, 43
	v_cvt_pk_bf16_f32 v70, v70, v71
	v_cvt_pk_bf16_f32 v71, v72, v73
	v_cvt_pk_bf16_f32 v72, v66, v67
	v_add_u32_e32 v66, s4, v134
	v_ashrrev_i32_e32 v131, 31, v130
	v_ashrrev_i32_e32 v67, 31, v66
	v_readlane_b32 s4, v253, 44
	v_lshlrev_b64 v[130:131], 11, v[130:131]
	v_ashrrev_i32_e32 v133, 31, v132
	v_lshlrev_b64 v[66:67], 11, v[66:67]
	v_cvt_pk_bf16_f32 v46, v46, v47
	v_cvt_pk_bf16_f32 v47, v48, v49
	v_cvt_pk_bf16_f32 v48, v42, v43
	v_add_u32_e32 v42, s4, v134
	v_lshl_add_u64 v[130:131], s[0:1], 0, v[130:131]
	v_cvt_pk_bf16_f32 v126, v126, v127
	v_cvt_pk_bf16_f32 v127, v128, v129
	v_cvt_pk_bf16_f32 v128, v122, v123
	v_lshlrev_b64 v[122:123], 1, v[132:133]
	v_ashrrev_i32_e32 v107, 31, v106
	v_lshl_add_u64 v[66:67], s[0:1], 0, v[66:67]
	v_ashrrev_i32_e32 v43, 31, v42
	v_readlane_b32 s4, v253, 45
	v_cvt_pk_bf16_f32 v129, v124, v125
	v_lshl_add_u64 v[124:125], v[130:131], 0, v[122:123]
	v_cvt_pk_bf16_f32 v113, v108, v109
	v_lshlrev_b64 v[106:107], 11, v[106:107]
	v_cvt_pk_bf16_f32 v62, v62, v63
	v_cvt_pk_bf16_f32 v63, v64, v65
	v_cvt_pk_bf16_f32 v64, v58, v59
	v_lshl_add_u64 v[58:59], v[66:67], 0, v[122:123]
	v_cvt_pk_bf16_f32 v49, v44, v45
	v_lshlrev_b64 v[42:43], 11, v[42:43]
	v_cvt_pk_bf16_f32 v30, v30, v31
	v_cvt_pk_bf16_f32 v31, v32, v33
	v_cvt_pk_bf16_f32 v32, v26, v27
	v_add_u32_e32 v26, s4, v134
	flat_store_dwordx4 v[124:125], v[110:113] offset:256
	v_ashrrev_i32_e32 v91, 31, v90
	flat_store_dwordx4 v[58:59], v[46:49] offset:256
	v_lshl_add_u64 v[110:111], s[0:1], 0, v[106:107]
	v_ashrrev_i32_e32 v27, 31, v26
	v_lshl_add_u64 v[46:47], s[0:1], 0, v[42:43]
	v_readlane_b32 s4, v253, 47
	v_lshl_add_u64 v[110:111], v[110:111], 0, v[122:123]
	v_cvt_pk_bf16_f32 v97, v92, v93
	v_lshlrev_b64 v[90:91], 11, v[90:91]
	v_lshl_add_u64 v[46:47], v[46:47], 0, v[122:123]
	v_cvt_pk_bf16_f32 v33, v28, v29
	v_lshlrev_b64 v[26:27], 11, v[26:27]
	v_cvt_pk_bf16_f32 v14, v14, v15
	v_cvt_pk_bf16_f32 v15, v16, v17
	v_cvt_pk_bf16_f32 v16, v10, v11
	v_add_u32_e32 v10, s4, v134
	flat_store_dwordx4 v[110:111], v[94:97] offset:256
	v_ashrrev_i32_e32 v75, 31, v74
	flat_store_dwordx4 v[46:47], v[30:33] offset:256
	v_lshl_add_u64 v[94:95], s[0:1], 0, v[90:91]
	v_ashrrev_i32_e32 v11, 31, v10
	v_lshl_add_u64 v[30:31], s[0:1], 0, v[26:27]
	v_lshl_add_u64 v[94:95], v[94:95], 0, v[122:123]
	v_cvt_pk_bf16_f32 v81, v76, v77
	v_lshlrev_b64 v[74:75], 11, v[74:75]
	v_lshl_add_u64 v[30:31], v[30:31], 0, v[122:123]
	v_cvt_pk_bf16_f32 v17, v12, v13
	v_lshlrev_b64 v[10:11], 11, v[10:11]
	flat_store_dwordx4 v[94:95], v[78:81] offset:256
	flat_store_dwordx4 v[30:31], v[14:17] offset:256
	v_cvt_pk_bf16_f32 v106, v118, v119
	v_lshl_add_u64 v[78:79], s[0:1], 0, v[74:75]
	v_lshl_add_u64 v[14:15], s[0:1], 0, v[10:11]
	v_cvt_pk_bf16_f32 v107, v120, v121
	v_cvt_pk_bf16_f32 v108, v114, v115
	v_cvt_pk_bf16_f32 v109, v116, v117
	v_cvt_pk_bf16_f32 v90, v102, v103
	v_cvt_pk_bf16_f32 v91, v104, v105
	v_cvt_pk_bf16_f32 v92, v98, v99
	v_cvt_pk_bf16_f32 v93, v100, v101
	v_cvt_pk_bf16_f32 v74, v86, v87
	v_cvt_pk_bf16_f32 v75, v88, v89
	v_cvt_pk_bf16_f32 v76, v82, v83
	v_cvt_pk_bf16_f32 v77, v84, v85
	v_lshl_add_u64 v[78:79], v[78:79], 0, v[122:123]
	v_cvt_pk_bf16_f32 v73, v68, v69
	v_cvt_pk_bf16_f32 v65, v60, v61
	v_cvt_pk_bf16_f32 v42, v54, v55
	v_cvt_pk_bf16_f32 v43, v56, v57
	v_cvt_pk_bf16_f32 v44, v50, v51
	v_cvt_pk_bf16_f32 v45, v52, v53
	v_cvt_pk_bf16_f32 v26, v38, v39
	v_cvt_pk_bf16_f32 v27, v40, v41
	v_cvt_pk_bf16_f32 v28, v34, v35
	v_cvt_pk_bf16_f32 v29, v36, v37
	v_cvt_pk_bf16_f32 v10, v22, v23
	v_cvt_pk_bf16_f32 v11, v24, v25
	v_cvt_pk_bf16_f32 v12, v18, v19
	v_cvt_pk_bf16_f32 v13, v20, v21
	v_lshl_add_u64 v[14:15], v[14:15], 0, v[122:123]
	v_cvt_pk_bf16_f32 v6, v6, v7
	v_cvt_pk_bf16_f32 v7, v8, v9
	v_cvt_pk_bf16_f32 v8, v2, v3
	v_cvt_pk_bf16_f32 v9, v4, v5
	flat_store_dwordx4 v[124:125], v[126:129]
	flat_store_dwordx4 v[110:111], v[106:109]
	flat_store_dwordx4 v[94:95], v[90:93]
	flat_store_dwordx4 v[78:79], v[74:77]
	flat_store_dwordx4 v[78:79], v[70:73] offset:256
	flat_store_dwordx4 v[58:59], v[62:65]
	flat_store_dwordx4 v[46:47], v[42:45]
	flat_store_dwordx4 v[30:31], v[26:29]
	flat_store_dwordx4 v[14:15], v[10:13]
	flat_store_dwordx4 v[14:15], v[6:9] offset:256
	s_mov_b32 s0, s91
	s_waitcnt vmcnt(0)
	s_barrier
	s_mov_b32 s64, 0
	s_waitcnt vmcnt(0)
	s_waitcnt vmcnt(0) lgkmcnt(0)
	v_or_b32_e32 v0, s0, v230
	v_cmp_eq_u32_e32 vcc, 0, v0
	s_barrier
	s_and_saveexec_b64 s[0:1], vcc
	s_movk_i32 s66, 0x1e00
	s_mov_b32 s67, 0x800000
	s_cbranch_execz .LBB0_1190
	v_writelane_b32 v2, s4, 1
	v_writelane_b32 v2, s5, 2
	v_writelane_b32 v2, s6, 3
	v_writelane_b32 v2, s7, 4
	v_readlane_b32 s4, v251, 0
	v_readlane_b32 s5, v251, 1
	s_getreg_b32 s6, hwreg(HW_REG_XCC_ID, 0, 4)
	s_load_dword s7, s[4:5], 0x100
	s_load_dwordx2 s[4:5], s[4:5], 0xf0
	v_mov_b32_e32 v0, 0x20010
	ds_read_b32 v3, v0
	ds_read_b32 v4, v0 offset:4
	ds_read_b32 v5, v0 offset:8
	s_and_b32 s6, s6, 15
	s_lshl_b32 s6, s6, 8
	v_mov_b32_e32 v13, 0x3400
	v_mov_b32_e32 v8, 1
	v_mov_b32_e32 v14, 0
	s_waitcnt lgkmcnt(0)
	s_add_u32 s4, s4, 0xee42000
	s_addc_u32 s5, s5, 0
	v_mov_b32_e32 v6, s6
	v_add_u32_e32 v7, 0x400, v6
	v_add_u32_e32 v6, 0x1400, v6
	buffer_inv sc1
	global_atomic_add v9, v6, v8, s[4:5] sc0
	v_add_u32_e32 v10, 1, v5
	v_mul_lo_u32 v11, v10, v3
	v_mul_lo_u32 v12, v10, v4
	s_waitcnt vmcnt(0)
	v_add_u32_e32 v9, 1, v9
	v_cmp_eq_u32_e32 vcc, v9, v11
	s_cbranch_vccz .Lhb_poll_9
	buffer_wbl2 sc1
	s_waitcnt vmcnt(0)
	global_atomic_add v13, v8, s[4:5]

.LBB0_1212:
	v_writelane_b32 v2, s4, 1
	v_writelane_b32 v2, s5, 2
	v_writelane_b32 v2, s6, 3
	v_writelane_b32 v2, s7, 4
	v_readlane_b32 s4, v251, 0
	v_readlane_b32 s5, v251, 1
	s_getreg_b32 s6, hwreg(HW_REG_XCC_ID, 0, 4)
	s_load_dword s7, s[4:5], 0x100
	s_load_dwordx2 s[4:5], s[4:5], 0xf0
	v_mov_b32_e32 v0, 0x20010
	ds_read_b32 v3, v0
	ds_read_b32 v4, v0 offset:4
	ds_read_b32 v5, v0 offset:8
	s_and_b32 s6, s6, 15
	s_lshl_b32 s6, s6, 8
	v_mov_b32_e32 v13, 0x3400
	v_mov_b32_e32 v8, 1
	v_mov_b32_e32 v14, 0
	s_waitcnt lgkmcnt(0)
	s_add_u32 s4, s4, 0xee42000
	s_addc_u32 s5, s5, 0
	v_mov_b32_e32 v6, s6
	v_add_u32_e32 v7, 0x400, v6
	v_add_u32_e32 v6, 0x1400, v6
	buffer_inv sc1
	global_atomic_add v9, v6, v8, s[4:5] sc0
	v_add_u32_e32 v10, 1, v5
	v_mul_lo_u32 v11, v10, v3
	v_mul_lo_u32 v12, v10, v4
	s_waitcnt vmcnt(0)
	v_add_u32_e32 v9, 1, v9
	v_cmp_eq_u32_e32 vcc, v9, v11
	s_cbranch_vccz .Lhb_poll_10
	buffer_wbl2 sc1
	s_waitcnt vmcnt(0)
	global_atomic_add v13, v8, s[4:5]

.Lhb_done_10:
	ds_write_b32 v0, v10 offset:8
	v_readlane_b32 s4, v2, 1
	v_readlane_b32 s5, v2, 2
	v_readlane_b32 s6, v2, 3
	v_readlane_b32 s7, v2, 4
	s_waitcnt vmcnt(0) lgkmcnt(0)
	s_nop 4
	s_getpc_b64 s[98:99]
